# gate/up GEMM: SwiGLU epilogue with eight interleaved element chains; 5 of its 8 stores deferred into the next unit's K-loop (3 via spare LDS, 2 in registers), run 1
# baseline (speedup 1.0000x reference)
; __device__ __forceinline__ unsigned cvt_pk_bf16(float lo, float hi) { unsigned r; asm volatile("v_cvt_pk_bf16_f32 %0, %1, %2" : "=v"(r) : "v"(lo), "v"(hi)); return r; }
; #define PG8_WAIT_V(n) asm volatile("s_waitcnt vmcnt(" #n ")" ::: "memory")
; #define PG8_WAIT_L(n) asm volatile("s_waitcnt lgkmcnt(" #n ")" ::: "memory")
;     __device__ __forceinline__ void operator()(const f32x4 (&acc)[2][2][4][2], const Unit& u, int wr, int wc, int fr, int fq, const float (&rsv)[8]) const {
;     ...
;             for (int m = 0; m < 4; ++m) { bf16_t* rowp = O + (size_t)(row0 + ai * HALF + m * 16) * ldc + col0; float r[8]; const float rr = rsv[ai * 4 + m];
; #pragma unroll
;                 for (int n = 0; n < 2; ++n)
; #pragma unroll
;                     for (int j = 0; j < 4; ++j) { const float g = acc[ai][0][m][n][j] * rr, up = acc[ai][1][m][n][j] * rr;
;                         const float e = __builtin_amdgcn_exp2f(g * -1.4426950408889634f); r[n * 4 + j] = g * __builtin_amdgcn_rcpf(1.0f + e) * up; }
;                 u32x4 w; w.x = cvt_pk_bf16(r[0], r[1]); w.y = cvt_pk_bf16(r[2], r[3]); w.z = cvt_pk_bf16(r[4], r[5]); w.w = cvt_pk_bf16(r[6], r[7]);
;                 *(u32x4*)rowp = w; }
; template <class Epi, class Sched, bool ALIGN_EPI = false, bool SP2 = false>
; __device__ __forceinline__ void gemm_phase(PG8_LAS unsigned char* lds, const Gemm g, const Sched& S, const Epi& E, const int tid_in) {
;     ...
;         for (int t = 0; t < nt; t += 2) {
;             const bool last = (t == nt - 2);
;             const char* a1 = cA + (size_t)(t + 1) * kstep;
;             const char* a2 = last ? nA : cA + (size_t)(t + 2) * kstep; const char* b2 = last ? nB : cB + (size_t)(t + 2) * kstep;
;             const char* a3 = a2 + kstep; const char* b3 = b2 + kstep;
;             if (last && has_next) S.a_ready(nxt);
;             if constexpr (SP2) {
;             PG8_LDB(B0, 0, 0); PG8_LDB(B1, 0, 1); PG8_SCHED; PG8_LDA(At, 0, 0); PG8_STAGE(PG8_SA(1, 1), a1 + hstep, voffA);
;             PG8_WAIT_V(8); PG8_WAIT_L(0); PG8_BAR; PG8_MMA(0, 0, At, B0); PG8_MMA(0, 1, At, B1); PG8_BAR; PG8_SCHED;
;             PG8_LDA(At, 0, 1); PG8_STAGE(PG8_SB(0, 0), b2, voffB); PG8_STAGE(PG8_SB(0, 1), b2 + hstep, voffB); PG8_STAGE(PG8_SA(0, 0), a2, voffA);
;             PG8_WAIT_V(8); PG8_WAIT_L(0); PG8_BAR; PG8_MMA(1, 0, At, B0); PG8_MMA(1, 1, At, B1); PG8_BAR; PG8_SCHED;
.LBB0_622:
	s_add_u32 s62, s70, 0xfffc0080
	s_addc_u32 s63, s71, -1
	s_add_i32 s64, 0, 0x10000
	s_cmp_eq_u32 s61, 12
	s_cselect_b32 s75, s7, s63
	s_cselect_b32 s74, s43, s62
	v_add_u32_e32 v143, s64, v145
	s_cselect_b32 s73, s19, s60
	s_cselect_b32 s72, s58, s59
	s_add_i32 s76, 0, 0x14000
	ds_read_b128 v[160:163], v143
	ds_read_b128 v[164:167], v143 offset:1024
	ds_read_b128 v[168:171], v143 offset:2048
	ds_read_b128 v[172:175], v143 offset:3072
	v_add_u32_e32 v143, s76, v145
	ds_read_b128 v[176:179], v143
	ds_read_b128 v[180:183], v143 offset:1024
	ds_read_b128 v[184:187], v143 offset:2048
	ds_read_b128 v[188:191], v143 offset:3072
	v_lshl_add_u32 v232, s61, 9, v254
	ds_read_b128 v[246:249], v232
	v_lshl_add_u64 v[154:155], s[70:71], 0, v[136:137]
	s_add_i32 m0, s27, 0xc000
	ds_read_b128 v[192:195], v149
	ds_read_b128 v[196:199], v149 offset:1024
	ds_read_b128 v[200:203], v149 offset:2048
	ds_read_b128 v[204:207], v149 offset:3072
	ds_read_b128 v[208:211], v149 offset:4096
	ds_read_b128 v[212:215], v149 offset:5120
	ds_read_b128 v[216:219], v149 offset:6144
	ds_read_b128 v[220:223], v149 offset:7168
	global_load_lds_dwordx4 v[154:155], off
	v_lshl_add_u64 v[154:155], s[70:71], 0, v[138:139]
	s_add_i32 m0, s27, 0xe000
	s_nop 0
	global_load_lds_dwordx4 v[154:155], off
	s_waitcnt vmcnt(8)
	s_waitcnt lgkmcnt(0)
	s_cmp_lt_u32 s38, 2
	s_cbranch_scc1 .Lpkf_done
	s_cmp_gt_u32 s61, 8
	s_cbranch_scc1 .Lpkf_done
	s_cmp_eq_u32 s61, 0
	s_cbranch_scc1 .Lpkf_0
	s_cmp_eq_u32 s61, 2
	s_cbranch_scc1 .Lpkf_1
	s_cmp_eq_u32 s61, 4
	s_cbranch_scc1 .Lpkf_2
	s_cmp_eq_u32 s61, 6
	s_cbranch_scc1 .Lpkf_3
	v_add_co_u32_e32 v232, vcc, 0xf2000, v240
	v_addc_co_u32_e32 v233, vcc, 0, v241, vcc
	global_store_dwordx4 v[232:233], v[236:239], off
	s_branch .Lpkf_done
.Lpkf_3:
	v_add_co_u32_e32 v232, vcc, 0xdc000, v240
	v_addc_co_u32_e32 v233, vcc, 0, v241, vcc
	global_store_dwordx4 v[232:233], v[250:253], off
	s_branch .Lpkf_done
.Lpkf_2:
	v_add_co_u32_e32 v232, vcc, 0xc6000, v240
	v_addc_co_u32_e32 v233, vcc, 0, v241, vcc
	global_store_dwordx4 v[232:233], v[246:249], off
	s_branch .Lpkf_done
.Lpkf_1:
	v_add_co_u32_e32 v232, vcc, 0xb0000, v240
	v_addc_co_u32_e32 v233, vcc, 0, v241, vcc
	global_store_dwordx4 v[232:233], v[246:249], off
	s_branch .Lpkf_done
.Lpkf_0:
	v_add_co_u32_e32 v232, vcc, 0x42000, v240
	v_addc_co_u32_e32 v233, vcc, 0, v241, vcc
	global_store_dwordx4 v[232:233], v[246:249], off
.Lpkf_done:
	s_barrier
	s_setprio 1
	s_waitcnt lgkmcnt(0)
	v_mfma_f32_16x16x32_bf16 v[126:129], v[160:163], v[192:195], v[126:129]
	v_mfma_f32_16x16x32_bf16 v[118:121], v[168:171], v[192:195], v[118:121]
	v_mfma_f32_16x16x32_bf16 v[110:113], v[160:163], v[200:203], v[110:113]
	v_mfma_f32_16x16x32_bf16 v[102:105], v[168:171], v[200:203], v[102:105]
	v_mfma_f32_16x16x32_bf16 v[94:97], v[160:163], v[208:211], v[94:97]
	v_mfma_f32_16x16x32_bf16 v[86:89], v[168:171], v[208:211], v[86:89]
	v_mfma_f32_16x16x32_bf16 v[78:81], v[160:163], v[216:219], v[78:81]
	v_mfma_f32_16x16x32_bf16 v[70:73], v[168:171], v[216:219], v[70:73]
	v_mfma_f32_16x16x32_bf16 v[126:129], v[164:167], v[196:199], v[126:129]
	v_mfma_f32_16x16x32_bf16 v[118:121], v[172:175], v[196:199], v[118:121]
	v_mfma_f32_16x16x32_bf16 v[110:113], v[164:167], v[204:207], v[110:113]
	v_mfma_f32_16x16x32_bf16 v[102:105], v[172:175], v[204:207], v[102:105]
	v_mfma_f32_16x16x32_bf16 v[94:97], v[164:167], v[212:215], v[94:97]
	v_mfma_f32_16x16x32_bf16 v[86:89], v[172:175], v[212:215], v[86:89]
	v_mfma_f32_16x16x32_bf16 v[78:81], v[164:167], v[220:223], v[78:81]
	v_mfma_f32_16x16x32_bf16 v[70:73], v[172:175], v[220:223], v[70:73]
	s_setprio 0
	s_setprio 1
	v_mfma_f32_16x16x32_bf16 v[122:125], v[176:179], v[192:195], v[122:125]
	v_mfma_f32_16x16x32_bf16 v[114:117], v[184:187], v[192:195], v[114:117]
	v_mfma_f32_16x16x32_bf16 v[106:109], v[176:179], v[200:203], v[106:109]
	v_mfma_f32_16x16x32_bf16 v[98:101], v[184:187], v[200:203], v[98:101]
	v_mfma_f32_16x16x32_bf16 v[90:93], v[176:179], v[208:211], v[90:93]
	v_mfma_f32_16x16x32_bf16 v[82:85], v[184:187], v[208:211], v[82:85]
	v_mfma_f32_16x16x32_bf16 v[74:77], v[176:179], v[216:219], v[74:77]
	v_mfma_f32_16x16x32_bf16 v[66:69], v[184:187], v[216:219], v[66:69]
	v_mfma_f32_16x16x32_bf16 v[122:125], v[180:183], v[196:199], v[122:125]
	v_mfma_f32_16x16x32_bf16 v[114:117], v[188:191], v[196:199], v[114:117]
	v_mfma_f32_16x16x32_bf16 v[106:109], v[180:183], v[204:207], v[106:109]
	v_mfma_f32_16x16x32_bf16 v[98:101], v[188:191], v[204:207], v[98:101]
	v_mfma_f32_16x16x32_bf16 v[90:93], v[180:183], v[212:215], v[90:93]
	v_mfma_f32_16x16x32_bf16 v[82:85], v[188:191], v[212:215], v[82:85]
	v_mfma_f32_16x16x32_bf16 v[74:77], v[180:183], v[220:223], v[74:77]
	v_mfma_f32_16x16x32_bf16 v[66:69], v[188:191], v[220:223], v[66:69]
	s_setprio 0
	s_barrier
	s_add_i32 s62, s64, s21
	v_lshl_add_u64 v[154:155], s[72:73], 0, v[0:1]
	s_mov_b32 m0, s62
	ds_read_b128 v[192:195], v149 offset:16384
	ds_read_b128 v[196:199], v149 offset:17408
	ds_read_b128 v[200:203], v149 offset:18432
	ds_read_b128 v[204:207], v149 offset:19456
	ds_read_b128 v[208:211], v149 offset:20480
	ds_read_b128 v[212:215], v149 offset:21504
	ds_read_b128 v[216:219], v149 offset:22528
	ds_read_b128 v[220:223], v149 offset:23552
	global_load_lds_dwordx4 v[154:155], off
	s_add_i32 m0, s62, 0x2000
	s_add_u32 s62, s72, 0x40000
	v_lshl_add_u64 v[224:225], s[72:73], 0, v[130:131]
	s_addc_u32 s63, s73, 0
	s_add_i32 s64, s76, s21
	global_load_lds_dwordx4 v[224:225], off
	v_lshl_add_u64 v[226:227], s[62:63], 0, v[0:1]
	s_mov_b32 m0, s64
	v_lshl_add_u64 v[228:229], s[74:75], 0, v[132:133]
	global_load_lds_dwordx4 v[226:227], off
	v_lshl_add_u64 v[226:227], s[62:63], 0, v[130:131]
	s_add_i32 m0, s64, 0x2000
	s_nop 0
	global_load_lds_dwordx4 v[226:227], off
	v_lshl_add_u64 v[226:227], s[74:75], 0, v[134:135]
	s_mov_b32 m0, s27
	s_nop 0
	global_load_lds_dwordx4 v[226:227], off
	s_mov_b32 m0, s29
	s_nop 0
	global_load_lds_dwordx4 v[228:229], off
	s_cmp_lt_u32 s38, 2
	s_cbranch_scc1 .Lpkf_w8a
	s_cmp_gt_u32 s61, 8
	s_cbranch_scc1 .Lpkf_w8a
	s_waitcnt vmcnt(9)
	s_branch .Lpkf_wda

; #define PG8_STAGE(bufoff, gbase, voff) do { _Pragma("unroll") for (int _i = 0; _i < 2; ++_i) \
;         __builtin_amdgcn_global_load_lds((const unsigned*)((const char*)(gbase) + (voff)[_i]), (PG8_LAS unsigned*)(lds + (bufoff) + ldsw + _i * 8192), 16, 0, 0); } while (0)
; #define PG8_LDA(dst, b, h) do { _Pragma("unroll") for (int m = 0; m < 4; ++m) _Pragma("unroll") for (int k = 0; k < 2; ++k) dst[m][k] = *(const PG8_LAS bf16x8*)(lds + PG8_SA(b, h) + aoff + m * 2048 + k * 1024); } while (0)
; #define PG8_LDB(dst, b, h) do { _Pragma("unroll") for (int n = 0; n < 2; ++n) _Pragma("unroll") for (int k = 0; k < 2; ++k) dst[n][k] = *(const PG8_LAS bf16x8*)(lds + PG8_SB(b, h) + boff + n * 2048 + k * 1024); } while (0)
; #define PG8_MMA(ai, bj, At, Bt) do { __builtin_amdgcn_s_setprio(1); _Pragma("unroll") for (int m = 0; m < 4; ++m) _Pragma("unroll") for (int n = 0; n < 2; ++n) _Pragma("unroll") for (int k = 0; k < 2; ++k) \
;         acc[ai][bj][m][n] = __builtin_amdgcn_mfma_f32_16x16x32_bf16(Bt[n][k], At[m][k], acc[ai][bj][m][n], 0, 0, 0); __builtin_amdgcn_s_setprio(0); } while (0)
; #define PG8_WAIT_V(n) asm volatile("s_waitcnt vmcnt(" #n ")" ::: "memory")
; #define PG8_WAIT_L(n) asm volatile("s_waitcnt lgkmcnt(" #n ")" ::: "memory")
; #define PG8_BAR __builtin_amdgcn_s_barrier()
; #define PG8_SCHED __builtin_amdgcn_sched_barrier(0)
; template <class Epi, class Sched, bool ALIGN_EPI = false, bool SP2 = false>
; __device__ __forceinline__ void gemm_phase(PG8_LAS unsigned char* lds, const Gemm g, const Sched& S, const Epi& E, const int tid_in) {
;     ...
;             PG8_WAIT_V(8); PG8_WAIT_L(0); PG8_BAR; PG8_MMA(1, 0, At, B0); PG8_MMA(1, 1, At, B1); PG8_BAR; PG8_SCHED;
;             PG8_LDB(B0, 1, 0); PG8_LDB(B1, 1, 1); PG8_SCHED; PG8_LDA(At, 1, 0); PG8_STAGE(PG8_SA(0, 1), a2 + hstep, voffA);
;             PG8_WAIT_V(8); PG8_WAIT_L(0); PG8_BAR; PG8_MMA(0, 0, At, B0); PG8_MMA(0, 1, At, B1); PG8_BAR; PG8_SCHED;
.Lpkf_wda:
	s_waitcnt lgkmcnt(0)
	s_barrier
	s_setprio 1
	s_waitcnt lgkmcnt(0)
	v_mfma_f32_16x16x32_bf16 v[62:65], v[160:163], v[192:195], v[62:65]
	v_mfma_f32_16x16x32_bf16 v[54:57], v[168:171], v[192:195], v[54:57]
	v_mfma_f32_16x16x32_bf16 v[46:49], v[160:163], v[200:203], v[46:49]
	v_mfma_f32_16x16x32_bf16 v[38:41], v[168:171], v[200:203], v[38:41]
	v_mfma_f32_16x16x32_bf16 v[30:33], v[160:163], v[208:211], v[30:33]
	v_mfma_f32_16x16x32_bf16 v[22:25], v[168:171], v[208:211], v[22:25]
	v_mfma_f32_16x16x32_bf16 v[14:17], v[160:163], v[216:219], v[14:17]
	v_mfma_f32_16x16x32_bf16 v[6:9], v[168:171], v[216:219], v[6:9]
	v_mfma_f32_16x16x32_bf16 v[62:65], v[164:167], v[196:199], v[62:65]
	v_mfma_f32_16x16x32_bf16 v[54:57], v[172:175], v[196:199], v[54:57]
	v_mfma_f32_16x16x32_bf16 v[46:49], v[164:167], v[204:207], v[46:49]
	v_mfma_f32_16x16x32_bf16 v[38:41], v[172:175], v[204:207], v[38:41]
	v_mfma_f32_16x16x32_bf16 v[30:33], v[164:167], v[212:215], v[30:33]
	v_mfma_f32_16x16x32_bf16 v[22:25], v[172:175], v[212:215], v[22:25]
	v_mfma_f32_16x16x32_bf16 v[14:17], v[164:167], v[220:223], v[14:17]
	v_mfma_f32_16x16x32_bf16 v[6:9], v[172:175], v[220:223], v[6:9]
	s_setprio 0
	s_setprio 1
	v_mfma_f32_16x16x32_bf16 v[58:61], v[176:179], v[192:195], v[58:61]
	v_mfma_f32_16x16x32_bf16 v[50:53], v[184:187], v[192:195], v[50:53]
	v_mfma_f32_16x16x32_bf16 v[42:45], v[176:179], v[200:203], v[42:45]
	v_mfma_f32_16x16x32_bf16 v[34:37], v[184:187], v[200:203], v[34:37]
	v_mfma_f32_16x16x32_bf16 v[26:29], v[176:179], v[208:211], v[26:29]
	v_mfma_f32_16x16x32_bf16 v[18:21], v[184:187], v[208:211], v[18:21]
	v_mfma_f32_16x16x32_bf16 v[10:13], v[176:179], v[216:219], v[10:13]
	v_mfma_f32_16x16x32_bf16 v[2:5], v[184:187], v[216:219], v[2:5]
	v_mfma_f32_16x16x32_bf16 v[58:61], v[180:183], v[196:199], v[58:61]
	v_mfma_f32_16x16x32_bf16 v[50:53], v[188:191], v[196:199], v[50:53]
	v_mfma_f32_16x16x32_bf16 v[42:45], v[180:183], v[204:207], v[42:45]
	v_mfma_f32_16x16x32_bf16 v[34:37], v[188:191], v[204:207], v[34:37]
	v_mfma_f32_16x16x32_bf16 v[26:29], v[180:183], v[212:215], v[26:29]
	v_mfma_f32_16x16x32_bf16 v[18:21], v[188:191], v[212:215], v[18:21]
	v_mfma_f32_16x16x32_bf16 v[10:13], v[180:183], v[220:223], v[10:13]
	v_mfma_f32_16x16x32_bf16 v[2:5], v[188:191], v[220:223], v[2:5]
	s_setprio 0
	s_barrier
	s_add_i32 s64, 0, 0x18000
	v_add_u32_e32 v143, s64, v145
	s_add_i32 s76, 0, 0x1c000
	ds_read_b128 v[160:163], v143
	ds_read_b128 v[164:167], v143 offset:1024
	ds_read_b128 v[168:171], v143 offset:2048
	ds_read_b128 v[172:175], v143 offset:3072
	v_add_u32_e32 v143, s76, v145
	ds_read_b128 v[176:179], v143
	ds_read_b128 v[180:183], v143 offset:1024
	ds_read_b128 v[184:187], v143 offset:2048
	ds_read_b128 v[188:191], v143 offset:3072
	s_add_u32 s62, s74, 0x40000
	s_addc_u32 s63, s75, 0
	s_mov_b32 m0, s34
	v_lshl_add_u64 v[230:231], s[62:63], 0, v[134:135]
	ds_read_b128 v[192:195], v149 offset:32768
	ds_read_b128 v[196:199], v149 offset:33792
	ds_read_b128 v[200:203], v149 offset:34816
	ds_read_b128 v[204:207], v149 offset:35840
	ds_read_b128 v[208:211], v149 offset:36864
	ds_read_b128 v[212:215], v149 offset:37888
	ds_read_b128 v[216:219], v149 offset:38912
	ds_read_b128 v[220:223], v149 offset:39936
	global_load_lds_dwordx4 v[230:231], off
	v_lshl_add_u64 v[230:231], s[62:63], 0, v[132:133]
	s_mov_b32 m0, s35
	s_nop 0
	global_load_lds_dwordx4 v[230:231], off
	s_cmp_lt_u32 s38, 2
	s_cbranch_scc1 .Lpkf_w8b
	s_cmp_gt_u32 s61, 8
	s_cbranch_scc1 .Lpkf_w8b
	s_waitcnt vmcnt(9)
	s_branch .Lpkf_wdb

; #define PG8_STAGE(bufoff, gbase, voff) do { _Pragma("unroll") for (int _i = 0; _i < 2; ++_i) \
;         __builtin_amdgcn_global_load_lds((const unsigned*)((const char*)(gbase) + (voff)[_i]), (PG8_LAS unsigned*)(lds + (bufoff) + ldsw + _i * 8192), 16, 0, 0); } while (0)
; #define PG8_LDA(dst, b, h) do { _Pragma("unroll") for (int m = 0; m < 4; ++m) _Pragma("unroll") for (int k = 0; k < 2; ++k) dst[m][k] = *(const PG8_LAS bf16x8*)(lds + PG8_SA(b, h) + aoff + m * 2048 + k * 1024); } while (0)
; #define PG8_MMA(ai, bj, At, Bt) do { __builtin_amdgcn_s_setprio(1); _Pragma("unroll") for (int m = 0; m < 4; ++m) _Pragma("unroll") for (int n = 0; n < 2; ++n) _Pragma("unroll") for (int k = 0; k < 2; ++k) \
;         acc[ai][bj][m][n] = __builtin_amdgcn_mfma_f32_16x16x32_bf16(Bt[n][k], At[m][k], acc[ai][bj][m][n], 0, 0, 0); __builtin_amdgcn_s_setprio(0); } while (0)
; #define PG8_WAIT_V(n) asm volatile("s_waitcnt vmcnt(" #n ")" ::: "memory")
; #define PG8_WAIT_L(n) asm volatile("s_waitcnt lgkmcnt(" #n ")" ::: "memory")
; #define PG8_BAR __builtin_amdgcn_s_barrier()
; #define PG8_SCHED __builtin_amdgcn_sched_barrier(0)
; template <class Epi, class Sched, bool ALIGN_EPI = false, bool SP2 = false>
; __device__ __forceinline__ void gemm_phase(PG8_LAS unsigned char* lds, const Gemm g, const Sched& S, const Epi& E, const int tid_in) {
;     ...
;             PG8_WAIT_V(8); PG8_WAIT_L(0); PG8_BAR; PG8_MMA(0, 0, At, B0); PG8_MMA(0, 1, At, B1); PG8_BAR; PG8_SCHED;
;             PG8_LDA(At, 1, 1); PG8_STAGE(PG8_SB(1, 0), b3, voffB); PG8_STAGE(PG8_SB(1, 1), b3 + hstep, voffB); PG8_STAGE(PG8_SA(1, 0), a3, voffA);
;             PG8_WAIT_V(8); PG8_WAIT_L(0); PG8_BAR; PG8_MMA(1, 0, At, B0); PG8_MMA(1, 1, At, B1); PG8_BAR; PG8_SCHED;
.Lpkf_wdb:
	s_waitcnt lgkmcnt(0)
	s_barrier
	s_setprio 1
	s_waitcnt lgkmcnt(0)
	v_mfma_f32_16x16x32_bf16 v[126:129], v[160:163], v[192:195], v[126:129]
	v_mfma_f32_16x16x32_bf16 v[118:121], v[168:171], v[192:195], v[118:121]
	v_mfma_f32_16x16x32_bf16 v[110:113], v[160:163], v[200:203], v[110:113]
	v_mfma_f32_16x16x32_bf16 v[102:105], v[168:171], v[200:203], v[102:105]
	v_mfma_f32_16x16x32_bf16 v[94:97], v[160:163], v[208:211], v[94:97]
	v_mfma_f32_16x16x32_bf16 v[86:89], v[168:171], v[208:211], v[86:89]
	v_mfma_f32_16x16x32_bf16 v[78:81], v[160:163], v[216:219], v[78:81]
	v_mfma_f32_16x16x32_bf16 v[70:73], v[168:171], v[216:219], v[70:73]
	v_mfma_f32_16x16x32_bf16 v[126:129], v[164:167], v[196:199], v[126:129]
	v_mfma_f32_16x16x32_bf16 v[118:121], v[172:175], v[196:199], v[118:121]
	v_mfma_f32_16x16x32_bf16 v[110:113], v[164:167], v[204:207], v[110:113]
	v_mfma_f32_16x16x32_bf16 v[102:105], v[172:175], v[204:207], v[102:105]
	v_mfma_f32_16x16x32_bf16 v[94:97], v[164:167], v[212:215], v[94:97]
	v_mfma_f32_16x16x32_bf16 v[86:89], v[172:175], v[212:215], v[86:89]
	v_mfma_f32_16x16x32_bf16 v[78:81], v[164:167], v[220:223], v[78:81]
	v_mfma_f32_16x16x32_bf16 v[70:73], v[172:175], v[220:223], v[70:73]
	s_setprio 0
	s_setprio 1
	v_mfma_f32_16x16x32_bf16 v[122:125], v[176:179], v[192:195], v[122:125]
	v_mfma_f32_16x16x32_bf16 v[114:117], v[184:187], v[192:195], v[114:117]
	v_mfma_f32_16x16x32_bf16 v[106:109], v[176:179], v[200:203], v[106:109]
	v_mfma_f32_16x16x32_bf16 v[98:101], v[184:187], v[200:203], v[98:101]
	v_mfma_f32_16x16x32_bf16 v[90:93], v[176:179], v[208:211], v[90:93]
	v_mfma_f32_16x16x32_bf16 v[82:85], v[184:187], v[208:211], v[82:85]
	v_mfma_f32_16x16x32_bf16 v[74:77], v[176:179], v[216:219], v[74:77]
	v_mfma_f32_16x16x32_bf16 v[66:69], v[184:187], v[216:219], v[66:69]
	v_mfma_f32_16x16x32_bf16 v[122:125], v[180:183], v[196:199], v[122:125]
	v_mfma_f32_16x16x32_bf16 v[114:117], v[188:191], v[196:199], v[114:117]
	v_mfma_f32_16x16x32_bf16 v[106:109], v[180:183], v[204:207], v[106:109]
	v_mfma_f32_16x16x32_bf16 v[98:101], v[188:191], v[204:207], v[98:101]
	v_mfma_f32_16x16x32_bf16 v[90:93], v[180:183], v[212:215], v[90:93]
	v_mfma_f32_16x16x32_bf16 v[82:85], v[188:191], v[212:215], v[82:85]
	v_mfma_f32_16x16x32_bf16 v[74:77], v[180:183], v[220:223], v[74:77]
	v_mfma_f32_16x16x32_bf16 v[66:69], v[188:191], v[220:223], v[66:69]
	s_setprio 0
	s_barrier
	s_add_i32 s62, s64, s21
	v_lshl_add_u64 v[154:155], v[154:155], 0, s[44:45]
	s_mov_b32 m0, s62
	ds_read_b128 v[192:195], v149 offset:49152
	ds_read_b128 v[196:199], v149 offset:50176
	ds_read_b128 v[200:203], v149 offset:51200
	ds_read_b128 v[204:207], v149 offset:52224
	ds_read_b128 v[208:211], v149 offset:53248
	ds_read_b128 v[212:215], v149 offset:54272
	ds_read_b128 v[216:219], v149 offset:55296
	ds_read_b128 v[220:223], v149 offset:56320
	global_load_lds_dwordx4 v[154:155], off
	s_add_i32 m0, s62, 0x2000
	s_add_u32 s62, s72, 0x40080
	v_lshl_add_u64 v[154:155], v[224:225], 0, s[44:45]
	s_addc_u32 s63, s73, 0
	s_add_i32 s64, s76, s21
	global_load_lds_dwordx4 v[154:155], off
	v_lshl_add_u64 v[154:155], s[62:63], 0, v[0:1]
	s_mov_b32 m0, s64
	s_nop 0
	global_load_lds_dwordx4 v[154:155], off
	v_lshl_add_u64 v[154:155], s[62:63], 0, v[130:131]
	s_add_i32 m0, s64, 0x2000
	s_nop 0
	global_load_lds_dwordx4 v[154:155], off
	v_lshl_add_u64 v[154:155], v[226:227], 0, s[44:45]
	s_mov_b32 m0, s36
	s_nop 0
	global_load_lds_dwordx4 v[154:155], off
	v_lshl_add_u64 v[154:155], v[228:229], 0, s[44:45]
	s_mov_b32 m0, s37
	s_nop 0
	global_load_lds_dwordx4 v[154:155], off
	s_waitcnt vmcnt(8)
	s_waitcnt lgkmcnt(0)
	s_barrier
	s_setprio 1
	s_waitcnt lgkmcnt(0)
	v_mfma_f32_16x16x32_bf16 v[62:65], v[160:163], v[192:195], v[62:65]
	v_mfma_f32_16x16x32_bf16 v[54:57], v[168:171], v[192:195], v[54:57]
	v_mfma_f32_16x16x32_bf16 v[46:49], v[160:163], v[200:203], v[46:49]
	v_mfma_f32_16x16x32_bf16 v[38:41], v[168:171], v[200:203], v[38:41]
	v_mfma_f32_16x16x32_bf16 v[30:33], v[160:163], v[208:211], v[30:33]
	v_mfma_f32_16x16x32_bf16 v[22:25], v[168:171], v[208:211], v[22:25]
	v_mfma_f32_16x16x32_bf16 v[14:17], v[160:163], v[216:219], v[14:17]
	v_mfma_f32_16x16x32_bf16 v[6:9], v[168:171], v[216:219], v[6:9]
	v_mfma_f32_16x16x32_bf16 v[62:65], v[164:167], v[196:199], v[62:65]
	v_mfma_f32_16x16x32_bf16 v[54:57], v[172:175], v[196:199], v[54:57]
	v_mfma_f32_16x16x32_bf16 v[46:49], v[164:167], v[204:207], v[46:49]
	v_mfma_f32_16x16x32_bf16 v[38:41], v[172:175], v[204:207], v[38:41]
	v_mfma_f32_16x16x32_bf16 v[30:33], v[164:167], v[212:215], v[30:33]
	v_mfma_f32_16x16x32_bf16 v[22:25], v[172:175], v[212:215], v[22:25]
	v_mfma_f32_16x16x32_bf16 v[14:17], v[164:167], v[220:223], v[14:17]
	v_mfma_f32_16x16x32_bf16 v[6:9], v[172:175], v[220:223], v[6:9]
	s_setprio 0
	s_setprio 1
	v_mfma_f32_16x16x32_bf16 v[58:61], v[176:179], v[192:195], v[58:61]
	v_mfma_f32_16x16x32_bf16 v[50:53], v[184:187], v[192:195], v[50:53]
	v_mfma_f32_16x16x32_bf16 v[42:45], v[176:179], v[200:203], v[42:45]
	v_mfma_f32_16x16x32_bf16 v[34:37], v[184:187], v[200:203], v[34:37]
	v_mfma_f32_16x16x32_bf16 v[26:29], v[176:179], v[208:211], v[26:29]
	v_mfma_f32_16x16x32_bf16 v[18:21], v[184:187], v[208:211], v[18:21]
	v_mfma_f32_16x16x32_bf16 v[10:13], v[176:179], v[216:219], v[10:13]
	v_mfma_f32_16x16x32_bf16 v[2:5], v[184:187], v[216:219], v[2:5]
	v_mfma_f32_16x16x32_bf16 v[58:61], v[180:183], v[196:199], v[58:61]
	v_mfma_f32_16x16x32_bf16 v[50:53], v[188:191], v[196:199], v[50:53]
	v_mfma_f32_16x16x32_bf16 v[42:45], v[180:183], v[204:207], v[42:45]
	v_mfma_f32_16x16x32_bf16 v[34:37], v[188:191], v[204:207], v[34:37]
	v_mfma_f32_16x16x32_bf16 v[26:29], v[180:183], v[212:215], v[26:29]
	v_mfma_f32_16x16x32_bf16 v[18:21], v[188:191], v[212:215], v[18:21]
	v_mfma_f32_16x16x32_bf16 v[10:13], v[180:183], v[220:223], v[10:13]
	v_mfma_f32_16x16x32_bf16 v[2:5], v[188:191], v[220:223], v[2:5]
	s_setprio 0
	s_barrier
	s_add_i32 s61, s61, 2
	s_add_u32 s70, s70, 0x100
	s_addc_u32 s71, s71, 0
	s_add_u32 s59, s59, 0x100
	s_addc_u32 s60, s60, 0
	s_cmp_gt_u32 s61, 13
	s_cbranch_scc0 .LBB0_622
	s_and_b64 vcc, exec, s[16:17]
	s_cbranch_vccz .LBB0_625
	s_barrier
; __device__ __forceinline__ unsigned cvt_pk_bf16(float lo, float hi) { unsigned r; asm volatile("v_cvt_pk_bf16_f32 %0, %1, %2" : "=v"(r) : "v"(lo), "v"(hi)); return r; }
;     __device__ __forceinline__ void operator()(const f32x4 (&acc)[2][2][4][2], const Unit& u, int wr, int wc, int fr, int fq, const float (&rsv)[8]) const {
;         const int row0 = u.pm * BM + wr * 64 + fr, col0 = u.pn * HALF + wc * 32 + 8 * fq;
; #pragma unroll
;         for (int ai = 0; ai < 2; ++ai)
; #pragma unroll
;             for (int m = 0; m < 4; ++m) { bf16_t* rowp = O + (size_t)(row0 + ai * HALF + m * 16) * ldc + col0; float r[8]; const float rr = rsv[ai * 4 + m];
; #pragma unroll
;                 for (int n = 0; n < 2; ++n)
; #pragma unroll
;                     for (int j = 0; j < 4; ++j) { const float g = acc[ai][0][m][n][j] * rr, up = acc[ai][1][m][n][j] * rr;
;                         const float e = __builtin_amdgcn_exp2f(g * -1.4426950408889634f); r[n * 4 + j] = g * __builtin_amdgcn_rcpf(1.0f + e) * up; }
;                 u32x4 w; w.x = cvt_pk_bf16(r[0], r[1]); w.y = cvt_pk_bf16(r[2], r[3]); w.z = cvt_pk_bf16(r[4], r[5]); w.w = cvt_pk_bf16(r[6], r[7]);
;                 *(u32x4*)rowp = w; }
.LBB0_625:
	v_mbcnt_lo_u32_b32 v254, -1, 0
	v_mbcnt_hi_u32_b32 v254, -1, v254
	v_lshlrev_b32_e32 v254, 4, v254
	v_mov_b32_e32 v234, s83
	v_mad_u32_u24 v254, v234, 48, v254
	v_add_u32_e32 v254, 0x20200, v254
	s_waitcnt vmcnt(8)
	v_lshl_or_b32 v160, s42, 7, v147
	v_ashrrev_i32_e32 v161, 31, v160
	v_mov_b64_e32 v[154:155], s[12:13]
	v_lshlrev_b64 v[164:165], 1, v[160:161]
	v_mad_i64_i32 v[162:163], s[42:43], v142, s65, v[154:155]
	v_mul_f32_e32 v126, v158, v126
	v_mul_f32_e32 v127, v158, v127
	v_mul_f32_e32 v128, v158, v128
	v_mul_f32_e32 v129, v158, v129
	v_mul_f32_e32 v118, v158, v118
	v_mul_f32_e32 v119, v158, v119
	v_mul_f32_e32 v120, v158, v120
	v_mul_f32_e32 v121, v158, v121
	v_mul_f32_e32 v122, v158, v122
	v_mul_f32_e32 v123, v158, v123
	v_mul_f32_e32 v124, v158, v124
	v_mul_f32_e32 v125, v158, v125
	v_mul_f32_e32 v114, v158, v114
	v_mul_f32_e32 v115, v158, v115
	v_mul_f32_e32 v116, v158, v116
	v_mul_f32_e32 v117, v158, v117
	v_mul_f32_e32 v168, 0xbfb8aa3b, v126
	v_mul_f32_e32 v169, 0xbfb8aa3b, v127
	v_mul_f32_e32 v170, 0xbfb8aa3b, v128
	v_mul_f32_e32 v171, 0xbfb8aa3b, v129
	v_mul_f32_e32 v172, 0xbfb8aa3b, v118
	v_mul_f32_e32 v173, 0xbfb8aa3b, v119
	v_mul_f32_e32 v174, 0xbfb8aa3b, v120
	v_mul_f32_e32 v175, 0xbfb8aa3b, v121
	v_exp_f32_e32 v168, v168
	v_exp_f32_e32 v169, v169
	v_exp_f32_e32 v170, v170
	v_exp_f32_e32 v171, v171
	v_exp_f32_e32 v172, v172
	v_exp_f32_e32 v173, v173
	v_exp_f32_e32 v174, v174
	v_exp_f32_e32 v175, v175
	v_add_f32_e32 v168, 1.0, v168
	v_add_f32_e32 v169, 1.0, v169
	v_add_f32_e32 v170, 1.0, v170
	v_add_f32_e32 v171, 1.0, v171
	v_add_f32_e32 v172, 1.0, v172
	v_add_f32_e32 v173, 1.0, v173
	v_add_f32_e32 v174, 1.0, v174
	v_add_f32_e32 v175, 1.0, v175
	v_rcp_f32_e32 v168, v168
	v_rcp_f32_e32 v169, v169
	v_rcp_f32_e32 v170, v170
	v_rcp_f32_e32 v171, v171
	v_rcp_f32_e32 v172, v172
	v_rcp_f32_e32 v173, v173
	v_rcp_f32_e32 v174, v174
	v_rcp_f32_e32 v175, v175
	v_mul_f32_e32 v126, v126, v168
	v_mul_f32_e32 v127, v127, v169
	v_mul_f32_e32 v128, v128, v170
	v_mul_f32_e32 v129, v129, v171
	v_mul_f32_e32 v118, v118, v172
	v_mul_f32_e32 v119, v119, v173
	v_mul_f32_e32 v120, v120, v174
	v_mul_f32_e32 v121, v121, v175
	v_mul_f32_e32 v126, v126, v122
	v_mul_f32_e32 v127, v127, v123
	v_mul_f32_e32 v128, v128, v124
	v_mul_f32_e32 v129, v129, v125
	v_mul_f32_e32 v118, v118, v114
	v_mul_f32_e32 v119, v119, v115
	v_mul_f32_e32 v120, v120, v116
	v_mul_f32_e32 v121, v121, v117
	v_lshl_add_u64 v[162:163], v[162:163], 0, v[164:165]
	v_cvt_pk_bf16_f32 v122, v126, v127
	v_cvt_pk_bf16_f32 v123, v128, v129
	v_cvt_pk_bf16_f32 v124, v118, v119
	v_cvt_pk_bf16_f32 v125, v120, v121
	global_store_dwordx4 v[162:163], v[122:125], off
	v_mov_b32_e32 v240, v162
	v_mov_b32_e32 v241, v163
	v_add_u32_e32 v176, 0x10, v142
	v_mad_i64_i32 v[166:167], s[42:43], v176, s65, v[154:155]
	v_mul_f32_e32 v110, v156, v110
	v_mul_f32_e32 v111, v156, v111
	v_mul_f32_e32 v112, v156, v112
	v_mul_f32_e32 v113, v156, v113
	v_mul_f32_e32 v102, v156, v102
	v_mul_f32_e32 v103, v156, v103
	v_mul_f32_e32 v104, v156, v104
	v_mul_f32_e32 v105, v156, v105
	v_mul_f32_e32 v106, v156, v106
	v_mul_f32_e32 v107, v156, v107
	v_mul_f32_e32 v108, v156, v108
	v_mul_f32_e32 v109, v156, v109
	v_mul_f32_e32 v98, v156, v98
	v_mul_f32_e32 v99, v156, v99
	v_mul_f32_e32 v100, v156, v100
	v_mul_f32_e32 v101, v156, v101
	v_mul_f32_e32 v168, 0xbfb8aa3b, v110
	v_mul_f32_e32 v169, 0xbfb8aa3b, v111
	v_mul_f32_e32 v170, 0xbfb8aa3b, v112
	v_mul_f32_e32 v171, 0xbfb8aa3b, v113
	v_mul_f32_e32 v172, 0xbfb8aa3b, v102
	v_mul_f32_e32 v173, 0xbfb8aa3b, v103
	v_mul_f32_e32 v174, 0xbfb8aa3b, v104
	v_mul_f32_e32 v175, 0xbfb8aa3b, v105
	v_exp_f32_e32 v168, v168
	v_exp_f32_e32 v169, v169
	v_exp_f32_e32 v170, v170
	v_exp_f32_e32 v171, v171
	v_exp_f32_e32 v172, v172
	v_exp_f32_e32 v173, v173
	v_exp_f32_e32 v174, v174
	v_exp_f32_e32 v175, v175
	v_add_f32_e32 v168, 1.0, v168
	v_add_f32_e32 v169, 1.0, v169
	v_add_f32_e32 v170, 1.0, v170
	v_add_f32_e32 v171, 1.0, v171
	v_add_f32_e32 v172, 1.0, v172
	v_add_f32_e32 v173, 1.0, v173
	v_add_f32_e32 v174, 1.0, v174
	v_add_f32_e32 v175, 1.0, v175
	v_rcp_f32_e32 v168, v168
	v_rcp_f32_e32 v169, v169
	v_rcp_f32_e32 v170, v170
	v_rcp_f32_e32 v171, v171
	v_rcp_f32_e32 v172, v172
	v_rcp_f32_e32 v173, v173
	v_rcp_f32_e32 v174, v174
	v_rcp_f32_e32 v175, v175
	v_mul_f32_e32 v110, v110, v168
	v_mul_f32_e32 v111, v111, v169
	v_mul_f32_e32 v112, v112, v170
	v_mul_f32_e32 v113, v113, v171
	v_mul_f32_e32 v102, v102, v172
	v_mul_f32_e32 v103, v103, v173
	v_mul_f32_e32 v104, v104, v174
	v_mul_f32_e32 v105, v105, v175
	v_mul_f32_e32 v110, v110, v106
	v_mul_f32_e32 v111, v111, v107
	v_mul_f32_e32 v112, v112, v108
	v_mul_f32_e32 v113, v113, v109
	v_mul_f32_e32 v102, v102, v98
	v_mul_f32_e32 v103, v103, v99
	v_mul_f32_e32 v104, v104, v100
	v_mul_f32_e32 v105, v105, v101
	v_lshl_add_u64 v[166:167], v[166:167], 0, v[164:165]
	v_cvt_pk_bf16_f32 v106, v110, v111
	v_cvt_pk_bf16_f32 v107, v112, v113
	v_cvt_pk_bf16_f32 v108, v102, v103
	v_cvt_pk_bf16_f32 v109, v104, v105
	global_store_dwordx4 v[166:167], v[106:109], off
	v_add_u32_e32 v176, 0x20, v142
	v_mad_i64_i32 v[162:163], s[42:43], v176, s65, v[154:155]
	v_mul_f32_e32 v94, v152, v94
	v_mul_f32_e32 v95, v152, v95
	v_mul_f32_e32 v96, v152, v96
	v_mul_f32_e32 v97, v152, v97
	v_mul_f32_e32 v86, v152, v86
	v_mul_f32_e32 v87, v152, v87
	v_mul_f32_e32 v88, v152, v88
	v_mul_f32_e32 v89, v152, v89
	v_mul_f32_e32 v90, v152, v90
	v_mul_f32_e32 v91, v152, v91
	v_mul_f32_e32 v92, v152, v92
	v_mul_f32_e32 v93, v152, v93
	v_mul_f32_e32 v82, v152, v82
	v_mul_f32_e32 v83, v152, v83
	v_mul_f32_e32 v84, v152, v84
	v_mul_f32_e32 v85, v152, v85
	v_mul_f32_e32 v168, 0xbfb8aa3b, v94
; __device__ __forceinline__ unsigned cvt_pk_bf16(float lo, float hi) { unsigned r; asm volatile("v_cvt_pk_bf16_f32 %0, %1, %2" : "=v"(r) : "v"(lo), "v"(hi)); return r; }
;     __device__ __forceinline__ void operator()(const f32x4 (&acc)[2][2][4][2], const Unit& u, int wr, int wc, int fr, int fq, const float (&rsv)[8]) const {
;     ...
;             for (int m = 0; m < 4; ++m) { bf16_t* rowp = O + (size_t)(row0 + ai * HALF + m * 16) * ldc + col0; float r[8]; const float rr = rsv[ai * 4 + m];
; #pragma unroll
;                 for (int n = 0; n < 2; ++n)
; #pragma unroll
;                     for (int j = 0; j < 4; ++j) { const float g = acc[ai][0][m][n][j] * rr, up = acc[ai][1][m][n][j] * rr;
;                         const float e = __builtin_amdgcn_exp2f(g * -1.4426950408889634f); r[n * 4 + j] = g * __builtin_amdgcn_rcpf(1.0f + e) * up; }
;                 u32x4 w; w.x = cvt_pk_bf16(r[0], r[1]); w.y = cvt_pk_bf16(r[2], r[3]); w.z = cvt_pk_bf16(r[4], r[5]); w.w = cvt_pk_bf16(r[6], r[7]);
;                 *(u32x4*)rowp = w; }
	v_mul_f32_e32 v169, 0xbfb8aa3b, v95
	v_mul_f32_e32 v170, 0xbfb8aa3b, v96
	v_mul_f32_e32 v171, 0xbfb8aa3b, v97
	v_mul_f32_e32 v172, 0xbfb8aa3b, v86
	v_mul_f32_e32 v173, 0xbfb8aa3b, v87
	v_mul_f32_e32 v174, 0xbfb8aa3b, v88
	v_mul_f32_e32 v175, 0xbfb8aa3b, v89
	v_exp_f32_e32 v168, v168
	v_exp_f32_e32 v169, v169
	v_exp_f32_e32 v170, v170
	v_exp_f32_e32 v171, v171
	v_exp_f32_e32 v172, v172
	v_exp_f32_e32 v173, v173
	v_exp_f32_e32 v174, v174
	v_exp_f32_e32 v175, v175
	v_add_f32_e32 v168, 1.0, v168
	v_add_f32_e32 v169, 1.0, v169
	v_add_f32_e32 v170, 1.0, v170
	v_add_f32_e32 v171, 1.0, v171
	v_add_f32_e32 v172, 1.0, v172
	v_add_f32_e32 v173, 1.0, v173
	v_add_f32_e32 v174, 1.0, v174
	v_add_f32_e32 v175, 1.0, v175
	v_rcp_f32_e32 v168, v168
	v_rcp_f32_e32 v169, v169
	v_rcp_f32_e32 v170, v170
	v_rcp_f32_e32 v171, v171
	v_rcp_f32_e32 v172, v172
	v_rcp_f32_e32 v173, v173
	v_rcp_f32_e32 v174, v174
	v_rcp_f32_e32 v175, v175
	v_mul_f32_e32 v94, v94, v168
	v_mul_f32_e32 v95, v95, v169
	v_mul_f32_e32 v96, v96, v170
	v_mul_f32_e32 v97, v97, v171
	v_mul_f32_e32 v86, v86, v172
	v_mul_f32_e32 v87, v87, v173
	v_mul_f32_e32 v88, v88, v174
	v_mul_f32_e32 v89, v89, v175
	v_mul_f32_e32 v94, v94, v90
	v_mul_f32_e32 v95, v95, v91
	v_mul_f32_e32 v96, v96, v92
	v_mul_f32_e32 v97, v97, v93
	v_mul_f32_e32 v86, v86, v82
	v_mul_f32_e32 v87, v87, v83
	v_mul_f32_e32 v88, v88, v84
	v_mul_f32_e32 v89, v89, v85
	v_lshl_add_u64 v[162:163], v[162:163], 0, v[164:165]
	v_cvt_pk_bf16_f32 v90, v94, v95
	v_cvt_pk_bf16_f32 v91, v96, v97
	v_cvt_pk_bf16_f32 v92, v86, v87
	v_cvt_pk_bf16_f32 v93, v88, v89
	global_store_dwordx4 v[162:163], v[90:93], off
	v_add_u32_e32 v176, 0x30, v142
	v_mad_i64_i32 v[166:167], s[42:43], v176, s65, v[154:155]
	v_mul_f32_e32 v78, v150, v78
	v_mul_f32_e32 v79, v150, v79
	v_mul_f32_e32 v80, v150, v80
	v_mul_f32_e32 v81, v150, v81
	v_mul_f32_e32 v70, v150, v70
	v_mul_f32_e32 v71, v150, v71
	v_mul_f32_e32 v72, v150, v72
	v_mul_f32_e32 v73, v150, v73
	v_mul_f32_e32 v74, v150, v74
	v_mul_f32_e32 v75, v150, v75
	v_mul_f32_e32 v76, v150, v76
	v_mul_f32_e32 v77, v150, v77
	v_mul_f32_e32 v66, v150, v66
	v_mul_f32_e32 v67, v150, v67
	v_mul_f32_e32 v68, v150, v68
	v_mul_f32_e32 v69, v150, v69
	v_mul_f32_e32 v168, 0xbfb8aa3b, v78
	v_mul_f32_e32 v169, 0xbfb8aa3b, v79
	v_mul_f32_e32 v170, 0xbfb8aa3b, v80
	v_mul_f32_e32 v171, 0xbfb8aa3b, v81
	v_mul_f32_e32 v172, 0xbfb8aa3b, v70
	v_mul_f32_e32 v173, 0xbfb8aa3b, v71
	v_mul_f32_e32 v174, 0xbfb8aa3b, v72
	v_mul_f32_e32 v175, 0xbfb8aa3b, v73
	v_exp_f32_e32 v168, v168
	v_exp_f32_e32 v169, v169
	v_exp_f32_e32 v170, v170
	v_exp_f32_e32 v171, v171
	v_exp_f32_e32 v172, v172
	v_exp_f32_e32 v173, v173
	v_exp_f32_e32 v174, v174
	v_exp_f32_e32 v175, v175
	v_add_f32_e32 v168, 1.0, v168
	v_add_f32_e32 v169, 1.0, v169
	v_add_f32_e32 v170, 1.0, v170
	v_add_f32_e32 v171, 1.0, v171
	v_add_f32_e32 v172, 1.0, v172
	v_add_f32_e32 v173, 1.0, v173
	v_add_f32_e32 v174, 1.0, v174
	v_add_f32_e32 v175, 1.0, v175
	v_rcp_f32_e32 v168, v168
	v_rcp_f32_e32 v169, v169
	v_rcp_f32_e32 v170, v170
	v_rcp_f32_e32 v171, v171
	v_rcp_f32_e32 v172, v172
	v_rcp_f32_e32 v173, v173
	v_rcp_f32_e32 v174, v174
	v_rcp_f32_e32 v175, v175
	v_mul_f32_e32 v78, v78, v168
	v_mul_f32_e32 v79, v79, v169
	v_mul_f32_e32 v80, v80, v170
	v_mul_f32_e32 v81, v81, v171
	v_mul_f32_e32 v70, v70, v172
	v_mul_f32_e32 v71, v71, v173
	v_mul_f32_e32 v72, v72, v174
	v_mul_f32_e32 v73, v73, v175
	v_mul_f32_e32 v78, v78, v74
	v_mul_f32_e32 v79, v79, v75
	v_mul_f32_e32 v80, v80, v76
	v_mul_f32_e32 v81, v81, v77
	v_mul_f32_e32 v70, v70, v66
	v_mul_f32_e32 v71, v71, v67
	v_mul_f32_e32 v72, v72, v68
	v_mul_f32_e32 v73, v73, v69
	v_lshl_add_u64 v[166:167], v[166:167], 0, v[164:165]
	v_cvt_pk_bf16_f32 v74, v78, v79
	v_cvt_pk_bf16_f32 v75, v80, v81
	v_cvt_pk_bf16_f32 v76, v70, v71
	v_cvt_pk_bf16_f32 v77, v72, v73
	ds_write_b128 v254, v[74:77]
	v_add_u32_e32 v176, 0x80, v142
	v_mad_i64_i32 v[162:163], s[42:43], v176, s65, v[154:155]
	v_mul_f32_e32 v62, v148, v62
	v_mul_f32_e32 v63, v148, v63
	v_mul_f32_e32 v64, v148, v64
	v_mul_f32_e32 v65, v148, v65
	v_mul_f32_e32 v54, v148, v54
	v_mul_f32_e32 v55, v148, v55
	v_mul_f32_e32 v56, v148, v56
	v_mul_f32_e32 v57, v148, v57
	v_mul_f32_e32 v58, v148, v58
	v_mul_f32_e32 v59, v148, v59
	v_mul_f32_e32 v60, v148, v60
	v_mul_f32_e32 v61, v148, v61
	v_mul_f32_e32 v50, v148, v50
	v_mul_f32_e32 v51, v148, v51
	v_mul_f32_e32 v52, v148, v52
	v_mul_f32_e32 v53, v148, v53
	v_mul_f32_e32 v168, 0xbfb8aa3b, v62
	v_mul_f32_e32 v169, 0xbfb8aa3b, v63
	v_mul_f32_e32 v170, 0xbfb8aa3b, v64
	v_mul_f32_e32 v171, 0xbfb8aa3b, v65
	v_mul_f32_e32 v172, 0xbfb8aa3b, v54
	v_mul_f32_e32 v173, 0xbfb8aa3b, v55
	v_mul_f32_e32 v174, 0xbfb8aa3b, v56
	v_mul_f32_e32 v175, 0xbfb8aa3b, v57
	v_exp_f32_e32 v168, v168
	v_exp_f32_e32 v169, v169
	v_exp_f32_e32 v170, v170
	v_exp_f32_e32 v171, v171
	v_exp_f32_e32 v172, v172
	v_exp_f32_e32 v173, v173
	v_exp_f32_e32 v174, v174
	v_exp_f32_e32 v175, v175
	v_add_f32_e32 v168, 1.0, v168
	v_add_f32_e32 v169, 1.0, v169
	v_add_f32_e32 v170, 1.0, v170
	v_add_f32_e32 v171, 1.0, v171
	v_add_f32_e32 v172, 1.0, v172
	v_add_f32_e32 v173, 1.0, v173
	v_add_f32_e32 v174, 1.0, v174
	v_add_f32_e32 v175, 1.0, v175
	v_rcp_f32_e32 v168, v168
	v_rcp_f32_e32 v169, v169
	v_rcp_f32_e32 v170, v170
	v_rcp_f32_e32 v171, v171
	v_rcp_f32_e32 v172, v172
	v_rcp_f32_e32 v173, v173
	v_rcp_f32_e32 v174, v174
	v_rcp_f32_e32 v175, v175
	v_mul_f32_e32 v62, v62, v168
	v_mul_f32_e32 v63, v63, v169
	v_mul_f32_e32 v64, v64, v170
	v_mul_f32_e32 v65, v65, v171
	v_mul_f32_e32 v54, v54, v172
	v_mul_f32_e32 v55, v55, v173
	v_mul_f32_e32 v56, v56, v174
	v_mul_f32_e32 v57, v57, v175
	v_mul_f32_e32 v62, v62, v58
; __device__ __forceinline__ unsigned cvt_pk_bf16(float lo, float hi) { unsigned r; asm volatile("v_cvt_pk_bf16_f32 %0, %1, %2" : "=v"(r) : "v"(lo), "v"(hi)); return r; }
;     __device__ __forceinline__ void operator()(const f32x4 (&acc)[2][2][4][2], const Unit& u, int wr, int wc, int fr, int fq, const float (&rsv)[8]) const {
;     ...
;             for (int m = 0; m < 4; ++m) { bf16_t* rowp = O + (size_t)(row0 + ai * HALF + m * 16) * ldc + col0; float r[8]; const float rr = rsv[ai * 4 + m];
; #pragma unroll
;                 for (int n = 0; n < 2; ++n)
; #pragma unroll
;                     for (int j = 0; j < 4; ++j) { const float g = acc[ai][0][m][n][j] * rr, up = acc[ai][1][m][n][j] * rr;
;                         const float e = __builtin_amdgcn_exp2f(g * -1.4426950408889634f); r[n * 4 + j] = g * __builtin_amdgcn_rcpf(1.0f + e) * up; }
;                 u32x4 w; w.x = cvt_pk_bf16(r[0], r[1]); w.y = cvt_pk_bf16(r[2], r[3]); w.z = cvt_pk_bf16(r[4], r[5]); w.w = cvt_pk_bf16(r[6], r[7]);
;                 *(u32x4*)rowp = w; }
	v_mul_f32_e32 v63, v63, v59
	v_mul_f32_e32 v64, v64, v60
	v_mul_f32_e32 v65, v65, v61
	v_mul_f32_e32 v54, v54, v50
	v_mul_f32_e32 v55, v55, v51
	v_mul_f32_e32 v56, v56, v52
	v_mul_f32_e32 v57, v57, v53
	v_lshl_add_u64 v[162:163], v[162:163], 0, v[164:165]
	v_cvt_pk_bf16_f32 v58, v62, v63
	v_cvt_pk_bf16_f32 v59, v64, v65
	v_cvt_pk_bf16_f32 v60, v54, v55
	v_cvt_pk_bf16_f32 v61, v56, v57
	ds_write_b128 v254, v[58:61] offset:1024
	v_add_u32_e32 v176, 0x90, v142
	v_mad_i64_i32 v[166:167], s[42:43], v176, s65, v[154:155]
	v_mul_f32_e32 v46, v146, v46
	v_mul_f32_e32 v47, v146, v47
	v_mul_f32_e32 v48, v146, v48
	v_mul_f32_e32 v49, v146, v49
	v_mul_f32_e32 v38, v146, v38
	v_mul_f32_e32 v39, v146, v39
	v_mul_f32_e32 v40, v146, v40
	v_mul_f32_e32 v41, v146, v41
	v_mul_f32_e32 v42, v146, v42
	v_mul_f32_e32 v43, v146, v43
	v_mul_f32_e32 v44, v146, v44
	v_mul_f32_e32 v45, v146, v45
	v_mul_f32_e32 v34, v146, v34
	v_mul_f32_e32 v35, v146, v35
	v_mul_f32_e32 v36, v146, v36
	v_mul_f32_e32 v37, v146, v37
	v_mul_f32_e32 v168, 0xbfb8aa3b, v46
	v_mul_f32_e32 v169, 0xbfb8aa3b, v47
	v_mul_f32_e32 v170, 0xbfb8aa3b, v48
	v_mul_f32_e32 v171, 0xbfb8aa3b, v49
	v_mul_f32_e32 v172, 0xbfb8aa3b, v38
	v_mul_f32_e32 v173, 0xbfb8aa3b, v39
	v_mul_f32_e32 v174, 0xbfb8aa3b, v40
	v_mul_f32_e32 v175, 0xbfb8aa3b, v41
	v_exp_f32_e32 v168, v168
	v_exp_f32_e32 v169, v169
	v_exp_f32_e32 v170, v170
	v_exp_f32_e32 v171, v171
	v_exp_f32_e32 v172, v172
	v_exp_f32_e32 v173, v173
	v_exp_f32_e32 v174, v174
	v_exp_f32_e32 v175, v175
	v_add_f32_e32 v168, 1.0, v168
	v_add_f32_e32 v169, 1.0, v169
	v_add_f32_e32 v170, 1.0, v170
	v_add_f32_e32 v171, 1.0, v171
	v_add_f32_e32 v172, 1.0, v172
	v_add_f32_e32 v173, 1.0, v173
	v_add_f32_e32 v174, 1.0, v174
	v_add_f32_e32 v175, 1.0, v175
	v_rcp_f32_e32 v168, v168
	v_rcp_f32_e32 v169, v169
	v_rcp_f32_e32 v170, v170
	v_rcp_f32_e32 v171, v171
	v_rcp_f32_e32 v172, v172
	v_rcp_f32_e32 v173, v173
	v_rcp_f32_e32 v174, v174
	v_rcp_f32_e32 v175, v175
	v_mul_f32_e32 v46, v46, v168
	v_mul_f32_e32 v47, v47, v169
	v_mul_f32_e32 v48, v48, v170
	v_mul_f32_e32 v49, v49, v171
	v_mul_f32_e32 v38, v38, v172
	v_mul_f32_e32 v39, v39, v173
	v_mul_f32_e32 v40, v40, v174
	v_mul_f32_e32 v41, v41, v175
	v_mul_f32_e32 v46, v46, v42
	v_mul_f32_e32 v47, v47, v43
	v_mul_f32_e32 v48, v48, v44
	v_mul_f32_e32 v49, v49, v45
	v_mul_f32_e32 v38, v38, v34
	v_mul_f32_e32 v39, v39, v35
	v_mul_f32_e32 v40, v40, v36
	v_mul_f32_e32 v41, v41, v37
	v_lshl_add_u64 v[166:167], v[166:167], 0, v[164:165]
	v_cvt_pk_bf16_f32 v42, v46, v47
	v_cvt_pk_bf16_f32 v43, v48, v49
	v_cvt_pk_bf16_f32 v44, v38, v39
	v_cvt_pk_bf16_f32 v45, v40, v41
	ds_write_b128 v254, v[42:45] offset:2048
	v_add_u32_e32 v176, 0xa0, v142
	v_mad_i64_i32 v[162:163], s[42:43], v176, s65, v[154:155]
	v_mul_f32_e32 v30, v144, v30
	v_mul_f32_e32 v31, v144, v31
	v_mul_f32_e32 v32, v144, v32
	v_mul_f32_e32 v33, v144, v33
	v_mul_f32_e32 v22, v144, v22
	v_mul_f32_e32 v23, v144, v23
	v_mul_f32_e32 v24, v144, v24
	v_mul_f32_e32 v25, v144, v25
	v_mul_f32_e32 v26, v144, v26
	v_mul_f32_e32 v27, v144, v27
	v_mul_f32_e32 v28, v144, v28
	v_mul_f32_e32 v29, v144, v29
	v_mul_f32_e32 v18, v144, v18
	v_mul_f32_e32 v19, v144, v19
	v_mul_f32_e32 v20, v144, v20
	v_mul_f32_e32 v21, v144, v21
	v_mul_f32_e32 v168, 0xbfb8aa3b, v30
	v_mul_f32_e32 v169, 0xbfb8aa3b, v31
	v_mul_f32_e32 v170, 0xbfb8aa3b, v32
	v_mul_f32_e32 v171, 0xbfb8aa3b, v33
	v_mul_f32_e32 v172, 0xbfb8aa3b, v22
	v_mul_f32_e32 v173, 0xbfb8aa3b, v23
	v_mul_f32_e32 v174, 0xbfb8aa3b, v24
	v_mul_f32_e32 v175, 0xbfb8aa3b, v25
	v_exp_f32_e32 v168, v168
	v_exp_f32_e32 v169, v169
	v_exp_f32_e32 v170, v170
	v_exp_f32_e32 v171, v171
	v_exp_f32_e32 v172, v172
	v_exp_f32_e32 v173, v173
	v_exp_f32_e32 v174, v174
	v_exp_f32_e32 v175, v175
	v_add_f32_e32 v168, 1.0, v168
	v_add_f32_e32 v169, 1.0, v169
	v_add_f32_e32 v170, 1.0, v170
	v_add_f32_e32 v171, 1.0, v171
	v_add_f32_e32 v172, 1.0, v172
	v_add_f32_e32 v173, 1.0, v173
	v_add_f32_e32 v174, 1.0, v174
	v_add_f32_e32 v175, 1.0, v175
	v_rcp_f32_e32 v168, v168
	v_rcp_f32_e32 v169, v169
	v_rcp_f32_e32 v170, v170
	v_rcp_f32_e32 v171, v171
	v_rcp_f32_e32 v172, v172
	v_rcp_f32_e32 v173, v173
	v_rcp_f32_e32 v174, v174
	v_rcp_f32_e32 v175, v175
	v_mul_f32_e32 v30, v30, v168
	v_mul_f32_e32 v31, v31, v169
	v_mul_f32_e32 v32, v32, v170
	v_mul_f32_e32 v33, v33, v171
	v_mul_f32_e32 v22, v22, v172
	v_mul_f32_e32 v23, v23, v173
	v_mul_f32_e32 v24, v24, v174
	v_mul_f32_e32 v25, v25, v175
	v_mul_f32_e32 v30, v30, v26
	v_mul_f32_e32 v31, v31, v27
	v_mul_f32_e32 v32, v32, v28
	v_mul_f32_e32 v33, v33, v29
	v_mul_f32_e32 v22, v22, v18
	v_mul_f32_e32 v23, v23, v19
	v_mul_f32_e32 v24, v24, v20
	v_mul_f32_e32 v25, v25, v21
	v_lshl_add_u64 v[162:163], v[162:163], 0, v[164:165]
	v_cvt_pk_bf16_f32 v26, v30, v31
	v_cvt_pk_bf16_f32 v27, v32, v33
	v_cvt_pk_bf16_f32 v28, v22, v23
	v_cvt_pk_bf16_f32 v29, v24, v25
	v_mov_b32_e32 v250, v26
	v_mov_b32_e32 v251, v27
	v_mov_b32_e32 v252, v28
	v_mov_b32_e32 v253, v29
	v_add_u32_e32 v176, 0xb0, v142
	v_mad_i64_i32 v[166:167], s[42:43], v176, s65, v[154:155]
	v_mul_f32_e32 v14, v140, v14
	v_mul_f32_e32 v15, v140, v15
; __device__ __forceinline__ unsigned cvt_pk_bf16(float lo, float hi) { unsigned r; asm volatile("v_cvt_pk_bf16_f32 %0, %1, %2" : "=v"(r) : "v"(lo), "v"(hi)); return r; }
; #define PG8_WAIT_V(n) asm volatile("s_waitcnt vmcnt(" #n ")" ::: "memory")
; #define PG8_BAR __builtin_amdgcn_s_barrier()
;     __device__ __forceinline__ void operator()(const f32x4 (&acc)[2][2][4][2], const Unit& u, int wr, int wc, int fr, int fq, const float (&rsv)[8]) const {
;     ...
;             for (int m = 0; m < 4; ++m) { bf16_t* rowp = O + (size_t)(row0 + ai * HALF + m * 16) * ldc + col0; float r[8]; const float rr = rsv[ai * 4 + m];
; #pragma unroll
;                 for (int n = 0; n < 2; ++n)
; #pragma unroll
;                     for (int j = 0; j < 4; ++j) { const float g = acc[ai][0][m][n][j] * rr, up = acc[ai][1][m][n][j] * rr;
;                         const float e = __builtin_amdgcn_exp2f(g * -1.4426950408889634f); r[n * 4 + j] = g * __builtin_amdgcn_rcpf(1.0f + e) * up; }
;                 u32x4 w; w.x = cvt_pk_bf16(r[0], r[1]); w.y = cvt_pk_bf16(r[2], r[3]); w.z = cvt_pk_bf16(r[4], r[5]); w.w = cvt_pk_bf16(r[6], r[7]);
;                 *(u32x4*)rowp = w; }
; template <class Epi, class Sched, bool ALIGN_EPI = false, bool SP2 = false>
; __device__ __forceinline__ void gemm_phase(PG8_LAS unsigned char* lds, const Gemm g, const Sched& S, const Epi& E, const int tid_in) {
;     ...
;     PG8_WAIT_V(0);
;     if constexpr (!ALIGN_EPI) { if (wr == 0) PG8_BAR; }
;     PG8_BAR;
	v_mul_f32_e32 v16, v140, v16
	v_mul_f32_e32 v17, v140, v17
	v_mul_f32_e32 v6, v140, v6
	v_mul_f32_e32 v7, v140, v7
	v_mul_f32_e32 v8, v140, v8
	v_mul_f32_e32 v9, v140, v9
	v_mul_f32_e32 v10, v140, v10
	v_mul_f32_e32 v11, v140, v11
	v_mul_f32_e32 v12, v140, v12
	v_mul_f32_e32 v13, v140, v13
	v_mul_f32_e32 v2, v140, v2
	v_mul_f32_e32 v3, v140, v3
	v_mul_f32_e32 v4, v140, v4
	v_mul_f32_e32 v5, v140, v5
	v_mul_f32_e32 v168, 0xbfb8aa3b, v14
	v_mul_f32_e32 v169, 0xbfb8aa3b, v15
	v_mul_f32_e32 v170, 0xbfb8aa3b, v16
	v_mul_f32_e32 v171, 0xbfb8aa3b, v17
	v_mul_f32_e32 v172, 0xbfb8aa3b, v6
	v_mul_f32_e32 v173, 0xbfb8aa3b, v7
	v_mul_f32_e32 v174, 0xbfb8aa3b, v8
	v_mul_f32_e32 v175, 0xbfb8aa3b, v9
	v_exp_f32_e32 v168, v168
	v_exp_f32_e32 v169, v169
	v_exp_f32_e32 v170, v170
	v_exp_f32_e32 v171, v171
	v_exp_f32_e32 v172, v172
	v_exp_f32_e32 v173, v173
	v_exp_f32_e32 v174, v174
	v_exp_f32_e32 v175, v175
	v_add_f32_e32 v168, 1.0, v168
	v_add_f32_e32 v169, 1.0, v169
	v_add_f32_e32 v170, 1.0, v170
	v_add_f32_e32 v171, 1.0, v171
	v_add_f32_e32 v172, 1.0, v172
	v_add_f32_e32 v173, 1.0, v173
	v_add_f32_e32 v174, 1.0, v174
	v_add_f32_e32 v175, 1.0, v175
	v_rcp_f32_e32 v168, v168
	v_rcp_f32_e32 v169, v169
	v_rcp_f32_e32 v170, v170
	v_rcp_f32_e32 v171, v171
	v_rcp_f32_e32 v172, v172
	v_rcp_f32_e32 v173, v173
	v_rcp_f32_e32 v174, v174
	v_rcp_f32_e32 v175, v175
	v_mul_f32_e32 v14, v14, v168
	v_mul_f32_e32 v15, v15, v169
	v_mul_f32_e32 v16, v16, v170
	v_mul_f32_e32 v17, v17, v171
	v_mul_f32_e32 v6, v6, v172
	v_mul_f32_e32 v7, v7, v173
	v_mul_f32_e32 v8, v8, v174
	v_mul_f32_e32 v9, v9, v175
	v_mul_f32_e32 v14, v14, v10
	v_mul_f32_e32 v15, v15, v11
	v_mul_f32_e32 v16, v16, v12
	v_mul_f32_e32 v17, v17, v13
	v_mul_f32_e32 v6, v6, v2
	v_mul_f32_e32 v7, v7, v3
	v_mul_f32_e32 v8, v8, v4
	v_mul_f32_e32 v9, v9, v5
	v_lshl_add_u64 v[166:167], v[166:167], 0, v[164:165]
	v_cvt_pk_bf16_f32 v10, v14, v15
	v_cvt_pk_bf16_f32 v11, v16, v17
	v_cvt_pk_bf16_f32 v12, v6, v7
	v_cvt_pk_bf16_f32 v13, v8, v9
	v_mov_b32_e32 v236, v10
	v_mov_b32_e32 v237, v11
	v_mov_b32_e32 v238, v12
	v_mov_b32_e32 v239, v13
	s_mov_b64 s[70:71], -1
	s_andn2_b64 vcc, exec, s[4:5]
	s_cbranch_vccnz .LBB0_618
	s_andn2_b64 vcc, exec, s[10:11]
	s_cbranch_vccnz .LBB0_617
	s_barrier
	s_branch .LBB0_617
.LBB0_628:
	ds_read_b128 v[246:249], v254
	v_add_co_u32_e32 v232, vcc, 0xdc000, v240
	v_addc_co_u32_e32 v233, vcc, 0, v241, vcc
	global_store_dwordx4 v[232:233], v[250:253], off
	v_add_co_u32_e32 v234, vcc, 0xf2000, v240
	v_addc_co_u32_e32 v235, vcc, 0, v241, vcc
	global_store_dwordx4 v[234:235], v[236:239], off
	s_nop 1
	ds_read_b128 v[250:253], v254 offset:1024
	ds_read_b128 v[236:239], v254 offset:2048
	s_waitcnt lgkmcnt(0)
	v_add_co_u32_e32 v232, vcc, 0x42000, v240
	v_addc_co_u32_e32 v233, vcc, 0, v241, vcc
	global_store_dwordx4 v[232:233], v[246:249], off
	v_add_co_u32_e32 v234, vcc, 0xb0000, v240
	v_addc_co_u32_e32 v235, vcc, 0, v241, vcc
	global_store_dwordx4 v[234:235], v[250:253], off
	s_nop 1
	v_add_co_u32_e32 v232, vcc, 0xc6000, v240
	v_addc_co_u32_e32 v233, vcc, 0, v241, vcc
	global_store_dwordx4 v[232:233], v[236:239], off
	s_waitcnt vmcnt(0)
	v_readlane_b32 s26, v255, 15
	s_barrier
	v_readlane_b32 s27, v255, 16
.LBB0_629:
	v_mov_b32_e32 v234, 0x2000
	v_mov_b32_e32 v235, 1
	v_mov_b64_e32 v[236:237], 0x5ff
	v_mov_b32_e32 v238, 0x3e38aa3b
	v_mov_b64_e32 v[232:233], 0x200
	v_mov_b64_e32 v[240:241], 0x1ff
	v_mov_b32_e32 v246, 0xff800000
	v_mov_b32_e32 v249, 0x358637bd
	v_mov_b32_e32 v252, 0x60000
	s_mov_b64 s[6:7], s[84:85]
	s_mov_b32 s1, -1
	s_getreg_b32 s0, hwreg(HW_REG_XCC_ID, 0, 4)
	s_nop 0
	v_mbcnt_lo_u32_b32 v0, s1, 0
	v_mbcnt_hi_u32_b32 v0, s1, v0
	v_or_b32_e32 v0, s83, v0
	s_waitcnt vmcnt(0)
	s_barrier
	v_cmp_eq_u32_e32 vcc, 0, v0
	s_mov_b64 s[4:5], exec
	s_and_b64 s[2:3], s[4:5], vcc
	v_mov_b32_e32 v219, 0x41b17218
	s_mov_b64 exec, s[2:3]
	s_cbranch_execz .LBB0_682
	v_readlane_b32 s1, v255, 7
	s_load_dwordx2 s[6:7], s[6:7], 0x90
	s_waitcnt vmcnt(0) expcnt(0) lgkmcnt(0)
	v_mov_b32_e32 v0, s1
	ds_read_b32 v3, v0
	v_readlane_b32 s1, v255, 8
	s_and_b32 s0, s0, 15
	s_waitcnt lgkmcnt(0)
	v_cmp_ne_u32_e32 vcc, 0, v3
	v_mov_b32_e32 v0, s1
	ds_read_b32 v0, v0
	s_cbranch_vccnz .LBB0_646
	s_add_u32 s10, s6, 0x4200
	s_addc_u32 s11, s7, 0
	s_add_u32 s12, s6, 0x4400
	s_addc_u32 s13, s7, 0
	s_add_u32 s14, s6, 0x4500
	s_addc_u32 s15, s7, 0
	s_add_u32 s16, s6, 0x4600
	s_addc_u32 s17, s7, 0
	s_add_u32 s18, s6, 0x4700
	s_addc_u32 s19, s7, 0
	s_add_u32 s22, s6, 0x4800
	s_addc_u32 s23, s7, 0
	s_add_u32 s68, s6, 0x4900
	s_addc_u32 s69, s7, 0
	s_add_u32 s70, s6, 0x4a00
	s_addc_u32 s71, s7, 0
	s_add_u32 s72, s6, 0x4b00
	s_addc_u32 s73, s7, 0
	s_add_u32 s74, s6, 0x4c00
	s_addc_u32 s75, s7, 0
	s_add_u32 s76, s6, 0x4d00
	s_addc_u32 s77, s7, 0
	s_add_u32 s78, s6, 0x4e00
	s_addc_u32 s79, s7, 0
	s_add_u32 s80, s6, 0x4f00
	s_addc_u32 s81, s7, 0
	s_add_u32 s82, s6, 0x5000
	s_addc_u32 s83, s7, 0
	s_add_u32 s84, s6, 0x5100
	s_addc_u32 s85, s7, 0
	s_add_u32 s86, s6, 0x5200
	s_addc_u32 s87, s7, 0
	s_add_u32 s88, s6, 0x5300
	s_addc_u32 s89, s7, 0
	s_mov_b32 s1, 1
	s_branch .LBB0_634

; __global__ void __launch_bounds__(NWAVES * 64, 2) hymba_fwd(Args args_unused) {
;     extern __shared__ __attribute__((aligned(16))) unsigned char lds[];
	.amdhsa_kernel _Z9hymba_fwd4Args
		.amdhsa_group_segment_fixed_size 16384
		.amdhsa_private_segment_fixed_size 0
		.amdhsa_kernarg_size 408
		.amdhsa_user_sgpr_count 2
		.amdhsa_user_sgpr_dispatch_ptr 0
		.amdhsa_user_sgpr_queue_ptr 0
		.amdhsa_user_sgpr_kernarg_segment_ptr 1
		.amdhsa_user_sgpr_dispatch_id 0
		.amdhsa_user_sgpr_kernarg_preload_length 0
		.amdhsa_user_sgpr_kernarg_preload_offset 0
		.amdhsa_user_sgpr_private_segment_size 0
		.amdhsa_uses_dynamic_stack 0
		.amdhsa_enable_private_segment 0
		.amdhsa_system_sgpr_workgroup_id_x 1
		.amdhsa_system_sgpr_workgroup_id_y 0
		.amdhsa_system_sgpr_workgroup_id_z 0
		.amdhsa_system_sgpr_workgroup_info 0
		.amdhsa_system_vgpr_workitem_id 2
		.amdhsa_next_free_vgpr 256
		.amdhsa_next_free_sgpr 98
		.amdhsa_accum_offset 256
		.amdhsa_reserve_vcc 1
		.amdhsa_float_round_mode_32 0
		.amdhsa_float_round_mode_16_64 0
		.amdhsa_float_denorm_mode_32 3
		.amdhsa_float_denorm_mode_16_64 3
		.amdhsa_dx10_clamp 1
		.amdhsa_ieee_mode 1
		.amdhsa_fp16_overflow 0
		.amdhsa_tg_split 0
		.amdhsa_exception_fp_ieee_invalid_op 0
		.amdhsa_exception_fp_denorm_src 0
		.amdhsa_exception_fp_ieee_div_zero 0
		.amdhsa_exception_fp_ieee_overflow 0
		.amdhsa_exception_fp_ieee_underflow 0
		.amdhsa_exception_fp_ieee_inexact 0
		.amdhsa_exception_int_div_zero 0
	.end_amdhsa_kernel

; __global__ void __launch_bounds__(NWAVES * 64, 2) hymba_fwd(Args args_unused) {
;     extern __shared__ __attribute__((aligned(16))) unsigned char lds[];
amdhsa.kernels:
  - .agpr_count:     0
    .args:
      - .offset:         0
        .size:           152
        .value_kind:     by_value
      - .offset:         152
        .size:           4
        .value_kind:     hidden_block_count_x
      - .offset:         156
        .size:           4
        .value_kind:     hidden_block_count_y
      - .offset:         160
        .size:           4
        .value_kind:     hidden_block_count_z
      - .offset:         164
        .size:           2
        .value_kind:     hidden_group_size_x
      - .offset:         166
        .size:           2
        .value_kind:     hidden_group_size_y
      - .offset:         168
        .size:           2
        .value_kind:     hidden_group_size_z
      - .offset:         170
        .size:           2
        .value_kind:     hidden_remainder_x
      - .offset:         172
        .size:           2
        .value_kind:     hidden_remainder_y
      - .offset:         174
        .size:           2
        .value_kind:     hidden_remainder_z
      - .offset:         192
        .size:           8
        .value_kind:     hidden_global_offset_x
      - .offset:         200
        .size:           8
        .value_kind:     hidden_global_offset_y
      - .offset:         208
        .size:           8
        .value_kind:     hidden_global_offset_z
      - .offset:         216
        .size:           2
        .value_kind:     hidden_grid_dims
      - .offset:         240
        .size:           8
        .value_kind:     hidden_multigrid_sync_arg
      - .offset:         272
        .size:           4
        .value_kind:     hidden_dynamic_lds_size
    .group_segment_fixed_size: 16384
    .kernarg_segment_align: 8
    .kernarg_segment_size: 408
    .language:       OpenCL C
    .language_version:
      - 2
      - 0
    .max_flat_workgroup_size: 512
    .name:           _Z9hymba_fwd4Args
    .private_segment_fixed_size: 0
    .sgpr_count:     104
    .sgpr_spill_count: 23
    .symbol:         _Z9hymba_fwd4Args.kd
    .uniform_work_group_size: 1
    .uses_dynamic_stack: false
    .vgpr_count:     256
    .vgpr_spill_count: 0
    .wavefront_size: 64
